# as v167 but each XCD leader issues its agent-scope invalidate after the top-level arrival atomic (overlapping the atomic's round trip) instead of before it; still completes before the XCD release
# speedup vs baseline: 1.0064x; 1.0038x over previous
.LBB0_200:
	s_andn2_saveexec_b64 s[4:5], s[4:5]
	s_cbranch_execz .LBB0_216
	v_mov_b32_e32 v1, s2
	v_add_co_u32_e32 v2, vcc, 0x3000, v1
	v_mov_b32_e32 v1, s3
	buffer_wbl2 sc1
	s_waitcnt vmcnt(0)
	v_addc_co_u32_e32 v3, vcc, 0, v1, vcc
	v_mov_b32_e32 v1, 1
	flat_atomic_add v1, v[2:3], v1 offset:1024 sc0
	buffer_inv sc1
	v_cvt_f32_u32_e32 v2, v0
	v_sub_u32_e32 v3, 0, v0
	s_add_u32 s4, s2, 0x3500
	s_addc_u32 s5, s3, 0
	v_rcp_iflag_f32_e32 v2, v2
	s_mov_b64 s[8:9], -1
	v_mul_f32_e32 v2, 0x4f7ffffe, v2
	v_cvt_u32_f32_e32 v2, v2
	v_mul_lo_u32 v3, v3, v2
	v_mul_hi_u32 v3, v2, v3
	v_add_u32_e32 v2, v2, v3
	s_waitcnt vmcnt(0) lgkmcnt(0)
	v_mul_hi_u32 v2, v1, v2
	v_mul_lo_u32 v4, v2, v0
	v_add_u32_e32 v3, 1, v1
	v_sub_u32_e32 v1, v1, v4
	v_add_u32_e32 v5, 1, v2
	v_cmp_ge_u32_e32 vcc, v1, v0
	v_sub_u32_e32 v4, v1, v0
	s_nop 0
	v_cndmask_b32_e32 v2, v2, v5, vcc
	v_cndmask_b32_e32 v1, v1, v4, vcc
	v_add_u32_e32 v4, 1, v2
	v_cmp_ge_u32_e32 vcc, v1, v0
	s_nop 1
	v_cndmask_b32_e32 v2, v2, v4, vcc
	v_mad_u64_u32 v[0:1], s[6:7], v0, v2, v[0:1]
	v_cmp_ne_u32_e32 vcc, v3, v0
	v_mov_b64_e32 v[0:1], s[4:5]
	s_and_saveexec_b64 s[6:7], vcc
	s_cbranch_execz .LBB0_213
	v_mov_b64_e32 v[0:1], s[4:5]
	flat_load_dword v0, v[0:1] sc1
	s_mov_b64 s[12:13], 0
	s_waitcnt vmcnt(0) lgkmcnt(0)
	v_cmp_eq_u32_e32 vcc, v0, v2
	s_and_saveexec_b64 s[10:11], vcc
	s_cbranch_execz .LBB0_212
	s_add_u32 s8, s2, 0x200
	s_addc_u32 s9, s3, 0
	s_mov_b32 s22, 1
	s_mov_b64 s[2:3], 0
	s_branch .LBB0_205

.LBB0_450:
	s_andn2_saveexec_b64 s[4:5], s[4:5]
	s_cbranch_execz .LBB0_466
	v_mov_b32_e32 v1, s2
	v_add_co_u32_e32 v2, vcc, 0x3000, v1
	v_mov_b32_e32 v1, s3
	buffer_wbl2 sc1
	s_waitcnt vmcnt(0)
	v_addc_co_u32_e32 v3, vcc, 0, v1, vcc
	flat_atomic_add v1, v[2:3], v176 offset:1024 sc0
	buffer_inv sc1
	v_cvt_f32_u32_e32 v2, v0
	v_sub_u32_e32 v3, 0, v0
	s_mov_b64 s[8:9], -1
	v_rcp_iflag_f32_e32 v2, v2
	s_nop 0
	v_mul_f32_e32 v2, 0x4f7ffffe, v2
	v_cvt_u32_f32_e32 v2, v2
	v_mul_lo_u32 v3, v3, v2
	v_mul_hi_u32 v3, v2, v3
	v_add_u32_e32 v2, v2, v3
	s_waitcnt vmcnt(0) lgkmcnt(0)
	v_mul_hi_u32 v2, v1, v2
	v_mul_lo_u32 v3, v2, v0
	v_sub_u32_e32 v3, v1, v3
	v_cmp_ge_u32_e32 vcc, v3, v0
	v_add_u32_e32 v4, 1, v2
	s_nop 0
	v_cndmask_b32_e32 v2, v2, v4, vcc
	v_sub_u32_e32 v4, v3, v0
	v_cndmask_b32_e32 v3, v3, v4, vcc
	v_cmp_ge_u32_e32 vcc, v3, v0
	v_add_u32_e32 v3, 1, v2
	s_nop 0
	v_cndmask_b32_e32 v2, v2, v3, vcc
	v_add_u32_e32 v3, 1, v1
	v_mad_u64_u32 v[0:1], s[4:5], v0, v2, v[0:1]
	s_add_u32 s4, s2, 0x3500
	s_addc_u32 s5, s3, 0
	v_cmp_ne_u32_e32 vcc, v3, v0
	v_mov_b64_e32 v[0:1], s[4:5]
	s_and_saveexec_b64 s[6:7], vcc
	s_cbranch_execz .LBB0_463
	v_mov_b64_e32 v[0:1], s[4:5]
	flat_load_dword v0, v[0:1] sc1
	s_mov_b64 s[12:13], 0
	s_waitcnt vmcnt(0) lgkmcnt(0)
	v_cmp_eq_u32_e32 vcc, v0, v2
	s_and_saveexec_b64 s[10:11], vcc
	s_cbranch_execz .LBB0_462
	s_add_u32 s8, s2, 0x200
	s_addc_u32 s9, s3, 0
	s_mov_b32 s22, 1
	s_mov_b64 s[2:3], 0
	s_branch .LBB0_455
